# plus: static s_setprio 1 for waves 0-3 during the attention phase 10 (no per-cluster priority toggles exist there)
# speedup vs baseline: 1.0016x; 1.0016x over previous
;   DI bf16_t* q1() const { return (bf16_t*)(ws + OFF_Q1); }
;   DI bf16_t* kn() const { return (bf16_t*)(ws + OFF_KN); }
;   DI bf16_t* kr() const { return (bf16_t*)(ws + OFF_KR); }
;   DI bf16_t* vt1() const { return (bf16_t*)(ws + OFF_VT1); }
; DI int otid() { int t = threadIdx.x; asm volatile("" : "+v"(t)); return t; }
; DI void mla_item(const Params& p, int b, int hh, int qt, char* smem) {
;   const int tid_ = otid(), lane = tid_ & 63, w = tid_ >> 6, l32 = lane & 31, g = lane >> 5;
;   f32x16 O[1][4]; float ls[1];
;   attn_core<192, 1, 128>(p.q1() + (size_t)b * S * 1536 + hh * 192, 1536, p.kn() + (size_t)b * S * 1024 + hh * 128, 1024, 128, p.kr() + (size_t)b * S * 64, 64,
;                          p.vt1() + (size_t)(b * 8 + hh) * 128 * S, qt * 256, 0, qt * 4 + 3, 0.07216878364870322f * LOG2E, -1e30f, 0.f, 0, smem, O, ls);
; DI void phase_attn1(const Params& p, char* smem) {
;   const int G = gridDim.x;
;   for (int round = 0; round * G < 512; ++round) {
;     const int j = (round & 1) ? (G - 1 - (int)blockIdx.x) : (int)blockIdx.x;
;     const int t = round * G + j;
;     if (t >= 512) continue;
;     const int qt = 15 - (t >> 5), bh = t & 31;
;     mla_item(p, bh >> 3, bh & 7, qt, smem);
;   }
.LBB0_1361:
	s_or_b64 exec, exec, s[0:1]
	s_not_b32 s0, s84
	s_add_i32 s27, s96, s0
	s_add_u32 s24, s22, 0x154c0000
	s_addc_u32 s25, s23, 0
	s_add_u32 s33, s22, 0x184c0000
	s_addc_u32 s40, s23, 0
	s_add_u32 s41, s22, 0x1a4c0000
	s_addc_u32 s44, s23, 0
	s_add_u32 s45, s22, 0x1a6c0000
	s_addc_u32 s46, s23, 0
	s_add_u32 s28, s22, 0x40c0000
	s_movk_i32 s34, 0xff00
	s_addc_u32 s29, s23, 0
	s_mov_b32 s31, 0
	s_movk_i32 s47, 0xc00
	v_mov_b32_e32 v0, 0
	s_mov_b32 s48, 0x2aaaaaab
	s_mov_b32 s35, -1
	s_movk_i32 s49, 0x190
	s_movk_i32 s50, 0x88
	s_movk_i32 s51, 0x6400
	s_mov_b32 s52, 0xf149f2ca
	s_mov_b32 s53, 0x3dd53b94
	s_mov_b32 s54, 0x41000000
	s_mov_b64 s[36:37], 0x20000
	s_mov_b64 s[38:39], 0x2000
	s_movk_i32 s55, 0x3300
	s_mov_b64 s[42:43], 0x80c0a00
	s_mov_b32 s56, 0x80c0000
	v_mov_b32_e32 v199, 0xf149f2ca
	v_mbcnt_hi_u32_b32 v198, -1, v207
	s_mov_b32 s0, 0
	s_mov_b32 s57, 0
	s_waitcnt lgkmcnt(0)
	s_barrier
	v_readfirstlane_b32 s98, v206
	s_nop 0
	s_lshr_b32 s98, s98, 8
	s_cmp_eq_u32 s98, 0
	s_cbranch_scc0 .Lattn_prio_skip
	s_setprio 1
.Lattn_prio_skip:
	s_branch .LBB0_1365

;   DI bf16_t* z() const { return (bf16_t*)(ws + OFF_Z); }
;   DI unsigned* bar() const { return (unsigned*)(ws + OFF_BAR); }
; __device__ __forceinline__ unsigned xb_ld(unsigned* p)              { return __hip_atomic_load(p, __ATOMIC_RELAXED, __HIP_MEMORY_SCOPE_AGENT); }
; __device__ __forceinline__ void xcd_barrier_complete(unsigned* bar, unsigned x, unsigned& nloc, unsigned& nx) {
;     const unsigned G = gridDim.x * gridDim.y * gridDim.z;
;     unsigned sum, cnt, mine, sp = 0u;
;     for (;;) {
;         sum = 0u; cnt = 0u; mine = 0u;
; #pragma unroll
;         for (unsigned j = 0; j < 16; ++j) { const unsigned c = xb_ld(&bar[XB_XCNT(j)]); sum += c; cnt += (c > 0u) ? 1u : 0u; mine = (j == x) ? c : mine; }
; __device__ __forceinline__ void xcd_barrier(const XcdBarrier& b) {
;     asm volatile("s_waitcnt vmcnt(0)" ::: "memory");
;     __syncthreads();
;     if (threadIdx.x == 0) {
;         unsigned* bar = b.bar;
;         __builtin_amdgcn_s_waitcnt(0);
;         unsigned nloc = b.st[0], nx = b.st[1];
;         if (nloc == 0u) { xcd_barrier_complete(bar, b.x, nloc, nx); b.st[0] = nloc; b.st[1] = nx; }
.LBB0_1578:
	s_waitcnt vmcnt(0)
	s_setprio 0
	s_barrier
	s_mov_b64 s[0:1], exec
	v_readlane_b32 s2, v252, 2
	v_readlane_b32 s3, v252, 3
	s_and_b64 s[2:3], s[0:1], s[2:3]
	s_mov_b64 exec, s[2:3]
	s_cbranch_execz .LBB0_1630
	v_mov_b32_e32 v0, 0
	s_waitcnt vmcnt(0) expcnt(0) lgkmcnt(0)
	ds_read_b32 v2, v0
	ds_read_b32 v1, v0 offset:4
	s_waitcnt lgkmcnt(1)
	v_cmp_ne_u32_e32 vcc, 0, v2
	s_cbranch_vccnz .LBB0_1594
	v_readlane_b32 s2, v252, 0
	s_mul_i32 s27, s97, s2
	s_add_u32 s2, s22, 0x1e6c1200
	s_addc_u32 s3, s23, 0
	s_add_u32 s6, s22, 0x1e6c1400
	s_addc_u32 s7, s23, 0
	s_add_u32 s8, s22, 0x1e6c1500
	s_addc_u32 s9, s23, 0
	s_add_u32 s10, s22, 0x1e6c1600
	s_addc_u32 s11, s23, 0
	s_add_u32 s12, s22, 0x1e6c1700
	s_addc_u32 s13, s23, 0
	s_add_u32 s14, s22, 0x1e6c1800
	s_addc_u32 s15, s23, 0
	s_add_u32 s16, s22, 0x1e6c1900
	s_addc_u32 s17, s23, 0
	s_add_u32 s18, s22, 0x1e6c1a00
	s_addc_u32 s19, s23, 0
	s_add_u32 s24, s22, 0x1e6c1b00
	s_addc_u32 s25, s23, 0
	s_add_u32 s30, s22, 0x1e6c1c00
	s_addc_u32 s31, s23, 0
	s_add_u32 s34, s22, 0x1e6c1d00
	s_addc_u32 s35, s23, 0
	s_add_u32 s36, s22, 0x1e6c1e00
	s_addc_u32 s37, s23, 0
	s_add_u32 s38, s22, 0x1e6c1f00
	s_addc_u32 s39, s23, 0
	s_add_u32 s40, s22, 0x1e6c2000
	s_addc_u32 s41, s23, 0
	s_add_u32 s42, s22, 0x1e6c2100
	s_addc_u32 s43, s23, 0
	s_add_u32 s44, s22, 0x1e6c2200
	s_addc_u32 s45, s23, 0
	s_add_u32 s46, s22, 0x1e6c2300
	s_mul_i32 s27, s27, s96
	s_addc_u32 s47, s23, 0
	s_mov_b32 s33, 1
	s_branch .LBB0_1582
